# v20 plus: attention-phase start fetches both bias tables with all loads in flight, overlapped with the first work-queue pop
# baseline (speedup 1.0000x reference)
; #define LAS __attribute__((address_space(3)))
; template <bool COOP>
; __global__ void __launch_bounds__(512, 2) mega(Args a) {
;     ...
;         LAS float* bias = (LAS float*)(lds + 81920);
;         for (int i = tid; i < NH * 257; i += 512) bias[i] = relb[i] * LOG2E;
;         __syncthreads();
.LBB0_323:
	v_lshlrev_b32_e32 v0, 2, v193
	global_load_dword v13, v0, s[52:53]
	global_load_dword v14, v0, s[52:53] offset:2048
	v_add_u32_e32 v1, 0x1000, v0
	global_load_dword v15, v1, s[52:53]
	global_load_dword v16, v1, s[52:53] offset:2048
	v_add_u32_e32 v1, 0x800, v193
	v_min_u32_e32 v1, 0x807, v1
	v_lshlrev_b32_e32 v1, 2, v1
	global_load_dword v17, v1, s[52:53]
	v_add_u32_e32 v5, 0, v193
	v_lshrrev_b32_e32 v6, 6, v5
	v_mul_u32_u24_e32 v6, 13, v6
	v_lshrrev_b32_e32 v6, 6, v6
	v_mul_u32_u24_e32 v7, 0x140, v6
	v_sub_u32_e32 v7, v5, v7
	v_min_u32_e32 v7, 0x100, v7
	v_mul_u32_u24_e32 v6, 0x101, v6
	v_add_u32_e32 v7, v7, v6
	v_lshlrev_b32_e32 v7, 2, v7
	global_load_dword v8, v7, s[52:53]
	v_add_u32_e32 v5, 512, v193
	v_lshrrev_b32_e32 v6, 6, v5
	v_mul_u32_u24_e32 v6, 13, v6
	v_lshrrev_b32_e32 v6, 6, v6
	v_mul_u32_u24_e32 v7, 0x140, v6
	v_sub_u32_e32 v7, v5, v7
	v_min_u32_e32 v7, 0x100, v7
	v_mul_u32_u24_e32 v6, 0x101, v6
	v_add_u32_e32 v7, v7, v6
	v_lshlrev_b32_e32 v7, 2, v7
	global_load_dword v9, v7, s[52:53]
	v_add_u32_e32 v5, 1024, v193
	v_lshrrev_b32_e32 v6, 6, v5
	v_mul_u32_u24_e32 v6, 13, v6
	v_lshrrev_b32_e32 v6, 6, v6
	v_mul_u32_u24_e32 v7, 0x140, v6
	v_sub_u32_e32 v7, v5, v7
	v_min_u32_e32 v7, 0x100, v7
	v_mul_u32_u24_e32 v6, 0x101, v6
	v_add_u32_e32 v7, v7, v6
	v_lshlrev_b32_e32 v7, 2, v7
	global_load_dword v10, v7, s[52:53]
	v_add_u32_e32 v5, 1536, v193
	v_lshrrev_b32_e32 v6, 6, v5
	v_mul_u32_u24_e32 v6, 13, v6
	v_lshrrev_b32_e32 v6, 6, v6
	v_mul_u32_u24_e32 v7, 0x140, v6
	v_sub_u32_e32 v7, v5, v7
	v_min_u32_e32 v7, 0x100, v7
	v_mul_u32_u24_e32 v6, 0x101, v6
	v_add_u32_e32 v7, v7, v6
	v_lshlrev_b32_e32 v7, 2, v7
	global_load_dword v11, v7, s[52:53]
	v_add_u32_e32 v5, 2048, v193
	v_lshrrev_b32_e32 v6, 6, v5
	v_mul_u32_u24_e32 v6, 13, v6
	v_lshrrev_b32_e32 v6, 6, v6
	v_mul_u32_u24_e32 v7, 0x140, v6
	v_sub_u32_e32 v7, v5, v7
	v_min_u32_e32 v7, 0x100, v7
	v_mul_u32_u24_e32 v6, 0x101, v6
	v_add_u32_e32 v7, v7, v6
	v_lshlrev_b32_e32 v7, 2, v7
	global_load_dword v12, v7, s[52:53]
	v_readlane_b32 s0, v255, 2
	v_readlane_b32 s1, v255, 3
	s_and_b64 vcc, exec, s[0:1]
	s_cbranch_vccnz .LBB0_327
	s_mov_b32 s10, 0
	s_movk_i32 s45, 0x400
	s_movk_i32 s92, 0x100
	s_movk_i32 s44, 0x1000
	s_branch .LBB0_328

; #define LAS __attribute__((address_space(3)))
; template <bool COOP>
; __global__ void __launch_bounds__(512, 2) mega(Args a) {
;     ...
;         for (int i = tid; i < NH * 257; i += 512) bias[i] = relb[i] * LOG2E;
;         __syncthreads();
;         LAS unsigned char* vlds = lds + wave * 9216;
;         AttnCtx C{QSB, KSB, VSB, QCB, KCB, VCB, ZG, OG, csk, csv, cck, ccv};
;         constexpr int NU = NB * NH * (TT / 32);
;         const int nq = (G % 8 == 0) ? 8 : 1, xq = (nq == 8) ? vcu / (G / 8) : 0, Wc = 1024 / nq, nSq = 256 / nq, nCq = NU / 2 / nq, nTot = nSq + 2 * nCq;
;         unsigned* ctr = (unsigned*)(ws + WS_CTL) + 4096 + 64 * xq;
;         unsigned nxt = 0;
;         if (lane == 0) nxt = __hip_atomic_fetch_add(ctr, 1u, __ATOMIC_RELAXED, __HIP_MEMORY_SCOPE_AGENT);
;         for (;;) {
;             const int idx = __builtin_amdgcn_readfirstlane((int)nxt);
;             if (idx >= nTot) break;
;             if (lane == 0) nxt = __hip_atomic_fetch_add(ctr, 1u, __ATOMIC_RELAXED, __HIP_MEMORY_SCOPE_AGENT);
.LBB0_332:
	v_writelane_b32 v255, s96, 14
	s_nop 1
	v_writelane_b32 v255, s97, 15
	v_writelane_b32 v255, s95, 8
	v_writelane_b32 v255, s84, 9
	s_nop 1
	v_writelane_b32 v255, s85, 10
	v_writelane_b32 v255, s82, 12
	s_nop 1
	v_writelane_b32 v255, s83, 13
	s_or_b64 exec, exec, s[4:5]
	s_waitcnt vmcnt(0)
	v_add_u32_e32 v5, 0x14000, v170
	v_mul_f32_e32 v13, 0x3fb8aa3b, v13
	v_mul_f32_e32 v14, 0x3fb8aa3b, v14
	v_mul_f32_e32 v15, 0x3fb8aa3b, v15
	v_mul_f32_e32 v16, 0x3fb8aa3b, v16
	v_mul_f32_e32 v17, 0x3fb8aa3b, v17
	ds_write_b32 v5, v13
	ds_write_b32 v5, v14 offset:2048
	ds_write_b32 v5, v15 offset:4096
	ds_write_b32 v5, v16 offset:6144
	ds_write_b32 v5, v17 offset:8192
	v_add_u32_e32 v5, 0x18000, v170
	v_mul_f32_e32 v8, 0x3fb8aa3b, v8
	v_mul_f32_e32 v9, 0x3fb8aa3b, v9
	v_mul_f32_e32 v10, 0x3fb8aa3b, v10
	v_mul_f32_e32 v11, 0x3fb8aa3b, v11
	v_mul_f32_e32 v12, 0x3fb8aa3b, v12
	ds_write_b32 v5, v8
	ds_write_b32 v5, v9 offset:2048
	ds_write_b32 v5, v10 offset:4096
	ds_write_b32 v5, v11 offset:6144
	ds_write_b32 v5, v12 offset:8192
	s_waitcnt lgkmcnt(0)
	s_barrier
	s_lshl_b32 s4, s44, 1
	s_or_b32 s93, s92, s4
	s_mul_i32 s4, s81, 0x2400
	s_add_i32 s94, s4, 0
	v_lshrrev_b32_e32 v0, 5, v192
	v_lshlrev_b32_e32 v3, 4, v192
	v_lshlrev_b32_e32 v7, 1, v193
	v_and_b32_e32 v4, 0xc0, v3
	v_lshl_add_u32 v6, v0, 8, s94
	v_and_b32_e32 v7, 32, v7
	v_lshlrev_b32_e32 v2, 3, v192
	v_add3_u32 v199, v6, v4, v7
	v_lshlrev_b32_e32 v4, 9, v193
	v_and_b32_e32 v196, 56, v2
	v_and_b32_e32 v201, 24, v2
	v_and_b32_e32 v4, 0x800, v4
	v_and_b32_e32 v2, 0x1c0, v2
	v_add3_u32 v203, s94, v4, v2
	v_and_b32_e32 v234, 48, v3
	v_and_b32_e32 v2, 0x70, v3
	v_cvt_f32_u32_e32 v3, s45
	s_add_u32 s52, s62, 0x7300000
	s_addc_u32 s53, s63, 0
	s_add_u32 s95, s62, 0xb500000
	v_rcp_iflag_f32_e32 v3, v3
	s_addc_u32 s96, s63, 0
	s_add_u32 s78, s62, 0xd600000
	s_addc_u32 s79, s63, 0
	v_mul_f32_e32 v3, 0x4f7ffffe, v3
	v_cvt_u32_f32_e32 v3, v3
	s_add_u32 s88, s62, 0xf700000
	v_lshlrev_b32_e32 v1, 6, v193
	s_addc_u32 s89, s63, 0
	v_and_b32_e32 v194, 0xe00, v1
	v_mov_b32_e32 v1, 0
	v_add_u32_e32 v235, s94, v2
	v_lshlrev_b32_e32 v237, 4, v0
	v_lshlrev_b32_e32 v238, 2, v0
	v_lshrrev_b32_e32 v2, 3, v192
	v_lshlrev_b32_e32 v0, 1, v196
	v_mul_u32_u24_e32 v239, 0x90, v2
	v_lshl_add_u64 v[204:205], s[52:53], 0, v[0:1]
	v_lshl_add_u64 v[206:207], s[58:59], 0, v[0:1]
	v_and_b32_e32 v2, 4, v2
	v_lshl_add_u64 v[208:209], s[78:79], 0, v[0:1]
	v_lshl_add_u64 v[210:211], s[88:89], 0, v[0:1]
	v_lshrrev_b32_e32 v0, 2, v193
	s_mul_i32 s97, s10, s45
	s_mul_i32 s83, s10, s92
	v_and_or_b32 v0, v0, 3, v2
	s_sub_i32 s10, 0, s45
	v_readfirstlane_b32 s11, v3
	v_and_b32_e32 v197, 31, v193
	v_lshlrev_b32_e32 v0, 6, v0
	s_mul_i32 s10, s10, s11
	v_add3_u32 v240, s94, v0, v7
	v_lshlrev_b32_e32 v0, 2, v196
	s_mul_hi_u32 s10, s11, s10
	v_sub_u32_e32 v241, v197, v2
	v_and_b32_e32 v2, 7, v193
	v_lshl_add_u64 v[212:213], s[68:69], 0, v[0:1]
	v_lshl_add_u64 v[214:215], s[70:71], 0, v[0:1]
	v_lshl_add_u64 v[216:217], s[72:73], 0, v[0:1]
	v_lshl_add_u64 v[218:219], s[74:75], 0, v[0:1]
	s_add_i32 s76, s11, s10
	v_lshlrev_b32_e32 v0, 7, v193
	v_lshlrev_b32_e32 v2, 4, v2
	s_movk_i32 s10, 0x1c00
	v_mov_b32_e32 v5, s94
	s_movk_i32 s82, 0x90
	v_lshrrev_b32_e32 v4, 1, v193
	v_and_or_b32 v0, v0, s10, v2
	s_mov_b64 s[8:9], 0xd600000
	v_mad_u32_u24 v236, v197, s82, v5
	v_and_b32_e32 v4, 16, v4
	v_lshl_add_u64 v[2:3], s[62:63], 0, v[0:1]
	v_mbcnt_lo_u32_b32 v0, -1, 0
	v_writelane_b32 v255, s81, 11
	s_mov_b32 s51, 0
	v_or_b32_e32 v198, 0x1000, v194
	v_or_b32_e32 v200, 0x2000, v194
	v_or_b32_e32 v202, 0x3000, v194
	v_cmp_gt_u32_e64 s[4:5], 32, v192
	v_cmp_lt_u32_e64 s[6:7], v238, v197
	v_lshl_add_u64 v[220:221], v[2:3], 0, s[8:9]
	s_mov_b32 s77, 0x8000
	s_mov_b32 s84, 0xc3160a50
	s_movk_i32 s85, 0x110
	v_add_u32_e32 v242, v236, v4
	v_mov_b32_e32 v243, 0xfc0
	v_mbcnt_hi_u32_b32 v244, -1, v0
	v_mov_b32_e32 v245, 0x200
	s_branch .LBB0_335
